# attention pass prologues de-serialised: all tile DMAs issued ahead of the |q|^2 reduction (counted waits), bias-table row store deferred past the Q wait
# speedup vs baseline: 1.0024x; 1.0024x over previous
; DI float bf2f(u16 v) { return __uint_as_float(((unsigned)v) << 16); }
; DI int v_st(int k, int c) { const int kk = (k & ~0xC) | ((k & 4) << 1) | ((k & 8) >> 1); return ((kk >> 3) * 4 + (c >> 5)) * 512 + ((kk & 7) * 32 + (c & 31)) * 2; }
; DI int v_rd_base(int lane) { return ((lane & 3) << 3) | (((lane >> 2) & 3) << 6) | (((lane >> 4) & 1) << 5) | (((lane >> 5) & 1) << 8); }
; template <int PROBE, int MODE>
; DI void dattn_body(const u16* __restrict__ Qb, const u16* __restrict__ Kh, const u16* __restrict__ Vh, u16* __restrict__ Ob, const u16* __restrict__ O1, float lam, const float* __restrict__ subg, int seq, int q0, float kmax2, char* lds) {
;     ...
;   const u16* Qw = Qb + (long)(rg * 32 + r32) * DM + hi * 8;
; #pragma unroll
;   for (int d0 = 0; d0 < 8; ++d0) qr[d0] = ld8(Qw + d0 * 16);
;   float q2 = 0.f;
; #pragma unroll
;   for (int d0 = 0; d0 < 8; ++d0)
; #pragma unroll
;     for (int e = 0; e < 8; ++e) { const float f = bf2f((u16)qr[d0][e]); q2 = fmaf(f, f, q2); }
;   { auto rr = __builtin_amdgcn_permlane32_swap(__float_as_uint(q2), __float_as_uint(q2), false, false); q2 = __uint_as_float(rr[0]) + __uint_as_float(rr[1]); }
;   const int sr = tid >> 4, sc = (tid & 15) * 8, vst0 = v_st(sr, sc), vst1 = v_st(32 + sr, sc), kst0 = KSWZ(sr, sc * 2), kst1 = KSWZ(32 + sr, sc * 2);
;   const int vb0 = (int)(uintptr_t)V_lds + kh * 16384 + v_rd_base(lane);
;   const int qpos = q0 + rg * 32 + r32;
;   char* pw = P_lds + wid * 2048 + lane * 32;
;   const char* pr = P_lds + (wid ^ 1) * 2048 + lane * 32;
;   const int wu = __builtin_amdgcn_readfirstlane(wid);
;   unsigned koff[2], voff[2];
; #pragma unroll
;   for (int i = 0; i < 2; ++i) {
;     const int a = i * 8192 + wid * 1024 + lane * 16;
;     { const int row = a >> 8, pch = (a & 255) >> 4, c = pch ^ (row & 7); koff[i] = (unsigned)(row * DM + c * 8) * 2u; }
;     { const int q = a >> 4, sub = q >> 5, kk = (sub >> 2) * 8 + ((q & 31) >> 2), k = (kk & ~0xC) | ((kk & 4) << 1) | ((kk & 8) >> 1), col = (sub & 3) * 32 + (q & 3) * 8;
;       voff[i] = (unsigned)(k * DM + col) * 2u; }
;   }
;     ...
;   f32x16 o[4] = {}; f32x16 S; float l_reg = 0.f; bf16x8 po0, po1; const int NT = seq / KVBLK;
;   KDMA(0, 0); VDMA(0, 0); KDMA(KVBLK, 1);
.LBB0_227:
	s_and_b32 s100, s2, 7
	s_bfe_u32 s101, s2, 0x50003
	s_lshr_b32 s4, s2, 8
	s_lshl_b32 s4, s4, 5
	s_add_i32 s101, s101, s4
	s_ff1_i32_b32 s4, s80
	s_lshr_b32 s5, s101, s4
	s_lshl_b32 s5, s5, 3
	s_add_i32 s5, s5, s100
	s_lshl_b32 s5, s5, s4
	s_add_i32 s100, s80, -1
	s_and_b32 s101, s101, s100
	s_add_i32 s100, s5, s101
	s_abs_i32 s1, s100
	v_readlane_b32 s4, v255, 39
	s_mul_hi_u32 s4, s1, s4
	s_mul_i32 s5, s4, s80
	s_sub_i32 s1, s1, s5
	s_ashr_i32 s0, s100, 31
	s_add_i32 s5, s4, 1
	s_sub_i32 s14, s1, s80
	s_cmp_ge_u32 s1, s80
	s_cselect_b32 s4, s5, s4
	s_cselect_b32 s1, s14, s1
	s_add_i32 s5, s4, 1
	s_cmp_ge_u32 s1, s80
	s_cselect_b32 s1, s5, s4
	s_xor_b32 s1, s1, s0
	s_sub_i32 s41, s1, s0
	s_movk_i32 s22, 0x80
	s_and_b32 s33, s41, 7
	s_barrier
	s_mov_b64 s[0:1], exec
	v_readlane_b32 s4, v255, 35
	v_readlane_b32 s5, v255, 36
	s_and_b64 s[4:5], s[0:1], s[4:5]
	s_mov_b64 exec, s[4:5]
	s_cbranch_execz .LBB0_229
	s_mul_i32 s4, s33, 0x104
	v_add_u32_e32 v0, s4, v190
	v_readlane_b32 s4, v251, 6
	v_ashrrev_i32_e32 v1, 31, v0
	v_readlane_b32 s5, v251, 7
	s_nop 1
	v_lshl_add_u64 v[0:1], v[0:1], 2, s[4:5]
	global_load_dword v18, v[0:1], off
.LBB0_229:
	s_or_b64 exec, exec, s[0:1]
	s_mul_i32 s0, s41, s80
	s_sub_i32 s18, s100, s0
	s_ashr_i32 s0, s41, 3
	s_ashr_i32 s1, s0, 31
	v_readlane_b32 s4, v255, 37
	s_lshl_b32 s87, s18, 7
	s_lshl_b64 s[14:15], s[0:1], s4
	s_ashr_i32 s1, s87, 31
	s_add_u32 s46, s14, s87
	s_addc_u32 s47, s15, s1
	s_lshl_b64 s[4:5], s[46:47], 12
	v_readlane_b32 s16, v251, 29
	v_readlane_b32 s17, v251, 30
	s_add_u32 s1, s16, s4
	s_addc_u32 s5, s17, s5
	s_lshl_b32 s19, s33, 9
	s_add_u32 s4, s1, s19
	s_addc_u32 s5, s5, 0
	s_lshl_b64 s[16:17], s[14:15], 12
	s_add_u32 s1, s36, s16
	s_addc_u32 s15, s37, s17
	s_add_u32 s14, s1, s19
	s_addc_u32 s15, s15, 0
	v_readlane_b32 s20, v253, 14
	v_readlane_b32 s21, v253, 15
	s_add_u32 s1, s20, s16
	s_addc_u32 s17, s21, s17
	s_add_u32 s16, s1, s19
	s_addc_u32 s17, s17, 0
	s_lshl_b32 s0, s0, 4
	s_lshl_b32 s1, s33, 1
	s_or_b32 s0, s0, s1
	s_ashr_i32 s1, s0, 31
	s_lshl_b64 s[0:1], s[0:1], 2
	v_readlane_b32 s20, v251, 45
	v_readlane_b32 s21, v251, 46
	s_add_u32 s38, s20, s0
	s_addc_u32 s39, s21, s1
	v_mov_b32_e32 v175, v179
	global_load_dword v0, v177, s[38:39]
	s_movk_i32 s0, 0xffe0
	v_ashrrev_i32_e32 v22, 2, v175
	v_bfi_b32 v2, s0, v22, v175
	v_ashrrev_i32_e32 v3, 31, v2
	v_bfe_u32 v24, v175, 5, 1
	v_lshlrev_b64 v[2:3], 12, v[2:3]
	v_lshl_add_u64 v[2:3], s[4:5], 0, v[2:3]
	v_lshlrev_b32_e32 v16, 4, v24
	v_mov_b32_e32 v17, v177
	v_lshl_add_u64 v[2:3], v[2:3], 0, v[16:17]
	global_load_dwordx4 v[82:85], v[2:3], off
	global_load_dwordx4 v[86:89], v[2:3], off offset:32
	global_load_dwordx4 v[90:93], v[2:3], off offset:64
	global_load_dwordx4 v[94:97], v[2:3], off offset:96
	global_load_dwordx4 v[98:101], v[2:3], off offset:128
	global_load_dwordx4 v[102:105], v[2:3], off offset:160
	global_load_dwordx4 v[106:109], v[2:3], off offset:192
	global_load_dwordx4 v[110:113], v[2:3], off offset:224
	v_and_b32_e32 v193, 63, v175
	v_ashrrev_i32_e32 v194, 6, v175
	v_lshlrev_b32_e32 v17, 4, v193
	v_lshlrev_b32_e32 v3, 10, v194
	v_or_b32_e32 v6, v3, v17
	v_and_b32_e32 v4, 15, v175
	v_ashrrev_i32_e32 v7, 8, v6
	v_bitop3_b32 v8, v7, v4, 7 bitop3:0x6c
	v_lshlrev_b32_e32 v7, 12, v7
	v_lshl_or_b32 v152, v8, 4, v7
	v_ashrrev_i32_e32 v7, 4, v6
	v_lshlrev_b32_e32 v8, 2, v194
	v_bfe_u32 v9, v7, 2, 2
	v_and_b32_e32 v8, 0xffff0, v8
	v_lshrrev_b32_e32 v7, 1, v7
	v_lshlrev_b32_e32 v10, 1, v194
	v_and_b32_e32 v7, 8, v7
	v_and_or_b32 v8, v10, 4, v8
	v_or3_b32 v7, v8, v9, v7
	v_lshrrev_b32_e32 v6, 3, v6
	v_and_b32_e32 v5, 48, v17
	v_and_b32_e32 v6, 0xc0, v6
	v_lshlrev_b32_e32 v7, 12, v7
	v_add_u32_e32 v3, 0x2000, v3
	v_or3_b32 v176, v7, v6, v5
	v_or_b32_e32 v6, v3, v17
	v_ashrrev_i32_e32 v7, 8, v6
	v_bitop3_b32 v4, v7, v4, 7 bitop3:0x6c
	v_lshlrev_b32_e32 v7, 12, v7
	v_readfirstlane_b32 s0, v194
	v_lshl_or_b32 v154, v4, 4, v7
	v_ashrrev_i32_e32 v4, 4, v6
	v_ashrrev_i32_e32 v3, 8, v3
	s_lshl_b32 s0, s0, 10
	s_add_i32 s95, 16, 0x10000
	v_bfe_u32 v7, v4, 2, 2
	v_and_b32_e32 v8, 0xffff0, v3
	v_lshrrev_b32_e32 v4, 1, v4
	v_lshrrev_b32_e32 v3, 1, v3
	s_add_i32 s82, s95, s0
	v_and_b32_e32 v4, 8, v4
	v_and_or_b32 v3, v3, 4, v8
	s_mov_b32 m0, s82
	v_or3_b32 v3, v3, v7, v4
	v_lshrrev_b32_e32 v4, 3, v6
	global_load_lds_dwordx4 v152, s[14:15]
	s_add_i32 m0, s82, 0x2000
	s_add_i32 s85, s0, 16
	v_and_b32_e32 v4, 0xc0, v4
	v_lshlrev_b32_e32 v3, 12, v3
	global_load_lds_dwordx4 v154, s[14:15]
	s_mov_b32 m0, s85
	v_or3_b32 v156, v3, v4, v5
	global_load_lds_dwordx4 v176, s[16:17]
	s_add_i32 m0, s85, 0x2000
	v_mov_b32_e32 v157, v177
	global_load_lds_dwordx4 v156, s[16:17]
	s_add_i32 m0, s85, 0x4000
	v_lshl_add_u64 v[4:5], s[16:17], 0, v[156:157]
	v_and_b32_e32 v192, 31, v175
	v_and_b32_e32 v196, 1, v194
	v_lshlrev_b32_e32 v195, 4, v175
	v_and_b32_e32 v20, 0x70, v195
	v_bitop3_b32 v199, v16, v20, 32 bitop3:0x36
	v_bitop3_b32 v200, v16, v20, 64 bitop3:0x36
	v_bitop3_b32 v202, v16, v20, s22 bitop3:0x36
	v_lshl_add_u64 v[8:9], s[16:17], 0, v[176:177]
	v_lshl_add_u64 v[8:9], v[8:9], 0, s[8:9]
	global_load_lds_dwordx4 v[8:9], off
	s_add_i32 m0, s85, 0x6000
	v_lshl_add_u64 v[8:9], v[4:5], 0, s[8:9]
	s_add_u32 s0, s14, 0x40000
	global_load_lds_dwordx4 v[8:9], off
	s_addc_u32 s1, s15, 0
	s_add_i32 m0, s85, 0x14000
	s_nop 0
	global_load_lds_dwordx4 v152, s[0:1]
	s_add_i32 m0, s85, 0x16000
	s_nop 0
	global_load_lds_dwordx4 v154, s[0:1]
	s_waitcnt vmcnt(8)
; DI float bf2f(u16 v) { return __uint_as_float(((unsigned)v) << 16); }
; template <int PROBE, int MODE>
; DI void dattn_body(const u16* __restrict__ Qb, const u16* __restrict__ Kh, const u16* __restrict__ Vh, u16* __restrict__ Ob, const u16* __restrict__ O1, float lam, const float* __restrict__ subg, int seq, int q0, float kmax2, char* lds) {
;     ...
;   float q2 = 0.f;
; #pragma unroll
;   for (int d0 = 0; d0 < 8; ++d0)
; #pragma unroll
;     for (int e = 0; e < 8; ++e) { const float f = bf2f((u16)qr[d0][e]); q2 = fmaf(f, f, q2); }
;   { auto rr = __builtin_amdgcn_permlane32_swap(__float_as_uint(q2), __float_as_uint(q2), false, false); q2 = __uint_as_float(rr[0]) + __uint_as_float(rr[1]); }
;     ...
;         if (tid < 258) ((float*)(lds + DA_TAB))[tid] = gtab[h * 260 + tid];
	v_cmp_gt_u32_e32 vcc, 0x102, v179
	s_and_saveexec_b64 s[0:1], vcc
	ds_write_b32 v174, v18
	s_mov_b64 exec, s[0:1]
	v_lshlrev_b32_e32 v1, 16, v82
	v_fma_f32 v1, v1, v1, 0
	v_and_b32_e32 v2, 0xffff0000, v82
	v_fmac_f32_e32 v1, v2, v2
	v_lshlrev_b32_e32 v2, 16, v83
	v_fmac_f32_e32 v1, v2, v2
	v_and_b32_e32 v2, 0xffff0000, v83
	v_fmac_f32_e32 v1, v2, v2
	v_lshlrev_b32_e32 v2, 16, v84
	v_fmac_f32_e32 v1, v2, v2
	v_and_b32_e32 v2, 0xffff0000, v84
	v_fmac_f32_e32 v1, v2, v2
	v_lshlrev_b32_e32 v2, 16, v85
	v_fmac_f32_e32 v1, v2, v2
	v_and_b32_e32 v2, 0xffff0000, v85
	v_fmac_f32_e32 v1, v2, v2
	v_lshlrev_b32_e32 v2, 16, v86
	v_fmac_f32_e32 v1, v2, v2
	v_and_b32_e32 v2, 0xffff0000, v86
	v_fmac_f32_e32 v1, v2, v2
	v_lshlrev_b32_e32 v2, 16, v87
	v_fmac_f32_e32 v1, v2, v2
	v_and_b32_e32 v2, 0xffff0000, v87
	v_fmac_f32_e32 v1, v2, v2
	v_lshlrev_b32_e32 v2, 16, v88
	v_fmac_f32_e32 v1, v2, v2
	v_and_b32_e32 v2, 0xffff0000, v88
	v_fmac_f32_e32 v1, v2, v2
	v_lshlrev_b32_e32 v2, 16, v89
	v_fmac_f32_e32 v1, v2, v2
	v_and_b32_e32 v2, 0xffff0000, v89
	v_fmac_f32_e32 v1, v2, v2
	v_lshlrev_b32_e32 v2, 16, v90
	v_fmac_f32_e32 v1, v2, v2
	v_and_b32_e32 v2, 0xffff0000, v90
	v_fmac_f32_e32 v1, v2, v2
	v_lshlrev_b32_e32 v2, 16, v91
	v_fmac_f32_e32 v1, v2, v2
	v_and_b32_e32 v2, 0xffff0000, v91
	v_fmac_f32_e32 v1, v2, v2
	v_lshlrev_b32_e32 v2, 16, v92
	v_fmac_f32_e32 v1, v2, v2
	v_and_b32_e32 v2, 0xffff0000, v92
	v_fmac_f32_e32 v1, v2, v2
	v_lshlrev_b32_e32 v2, 16, v93
	v_fmac_f32_e32 v1, v2, v2
	v_and_b32_e32 v2, 0xffff0000, v93
	v_fmac_f32_e32 v1, v2, v2
	v_lshlrev_b32_e32 v2, 16, v94
	v_fmac_f32_e32 v1, v2, v2
	v_and_b32_e32 v2, 0xffff0000, v94
	v_fmac_f32_e32 v1, v2, v2
	v_lshlrev_b32_e32 v2, 16, v95
	v_fmac_f32_e32 v1, v2, v2
	v_and_b32_e32 v2, 0xffff0000, v95
	v_fmac_f32_e32 v1, v2, v2
	v_lshlrev_b32_e32 v2, 16, v96
	v_fmac_f32_e32 v1, v2, v2
	v_and_b32_e32 v2, 0xffff0000, v96
	v_fmac_f32_e32 v1, v2, v2
	v_lshlrev_b32_e32 v2, 16, v97
	v_fmac_f32_e32 v1, v2, v2
	v_and_b32_e32 v2, 0xffff0000, v97
	v_fmac_f32_e32 v1, v2, v2
	v_lshlrev_b32_e32 v2, 16, v98
	v_fmac_f32_e32 v1, v2, v2
	v_and_b32_e32 v2, 0xffff0000, v98
	v_fmac_f32_e32 v1, v2, v2
	v_lshlrev_b32_e32 v2, 16, v99
	v_fmac_f32_e32 v1, v2, v2
	v_and_b32_e32 v2, 0xffff0000, v99
	v_fmac_f32_e32 v1, v2, v2
	v_lshlrev_b32_e32 v2, 16, v100
	v_fmac_f32_e32 v1, v2, v2
	v_and_b32_e32 v2, 0xffff0000, v100
	v_fmac_f32_e32 v1, v2, v2
	v_lshlrev_b32_e32 v2, 16, v101
	v_fmac_f32_e32 v1, v2, v2
	v_and_b32_e32 v2, 0xffff0000, v101
	v_fmac_f32_e32 v1, v2, v2
	v_lshlrev_b32_e32 v2, 16, v102
	v_fmac_f32_e32 v1, v2, v2
	v_and_b32_e32 v2, 0xffff0000, v102
	v_fmac_f32_e32 v1, v2, v2
	v_lshlrev_b32_e32 v2, 16, v103
	v_fmac_f32_e32 v1, v2, v2
	v_and_b32_e32 v2, 0xffff0000, v103
	v_fmac_f32_e32 v1, v2, v2
	v_lshlrev_b32_e32 v2, 16, v104
	v_fmac_f32_e32 v1, v2, v2
	v_and_b32_e32 v2, 0xffff0000, v104
	v_fmac_f32_e32 v1, v2, v2
	v_lshlrev_b32_e32 v2, 16, v105
	v_fmac_f32_e32 v1, v2, v2
	v_and_b32_e32 v2, 0xffff0000, v105
	v_fmac_f32_e32 v1, v2, v2
	v_lshlrev_b32_e32 v2, 16, v106
	v_fmac_f32_e32 v1, v2, v2
	v_and_b32_e32 v2, 0xffff0000, v106
	v_fmac_f32_e32 v1, v2, v2
	v_lshlrev_b32_e32 v2, 16, v107
	v_fmac_f32_e32 v1, v2, v2
	v_and_b32_e32 v2, 0xffff0000, v107
	v_fmac_f32_e32 v1, v2, v2
	v_lshlrev_b32_e32 v2, 16, v108
	v_fmac_f32_e32 v1, v2, v2
	v_and_b32_e32 v2, 0xffff0000, v108
	v_fmac_f32_e32 v1, v2, v2
	v_lshlrev_b32_e32 v2, 16, v109
	v_fmac_f32_e32 v1, v2, v2
	v_and_b32_e32 v2, 0xffff0000, v109
	v_fmac_f32_e32 v1, v2, v2
	v_lshlrev_b32_e32 v2, 16, v110
	v_fmac_f32_e32 v1, v2, v2
	v_and_b32_e32 v2, 0xffff0000, v110
	v_fmac_f32_e32 v1, v2, v2
	v_lshlrev_b32_e32 v2, 16, v111
	v_fmac_f32_e32 v1, v2, v2
	v_and_b32_e32 v2, 0xffff0000, v111
	v_fmac_f32_e32 v1, v2, v2
	v_lshlrev_b32_e32 v2, 16, v112
	v_fmac_f32_e32 v1, v2, v2
	v_and_b32_e32 v2, 0xffff0000, v112
	v_fmac_f32_e32 v1, v2, v2
	v_lshlrev_b32_e32 v2, 16, v113
	v_fmac_f32_e32 v1, v2, v2
	v_and_b32_e32 v2, 0xffff0000, v113
	v_fmac_f32_e32 v1, v2, v2
	v_mov_b32_e32 v2, v1
	s_nop 1
	v_permlane32_swap_b32_e32 v1, v2
	v_add_f32_e32 v1, v1, v2
	v_mov_b32_e32 v2, s76
	v_mul_f32_e32 v0, v0, v1
	s_waitcnt vmcnt(0)
	s_waitcnt vmcnt(0) lgkmcnt(0)
	s_barrier
; #define KDMA(k0, b) do { const char* g_ = (const char*)(Kh + (long)(k0) * DM); char* l_ = K_lds + (b) * 16384 + wu * 1024; \
;     DMA16(g_ + koff[0], l_); DMA16(g_ + koff[1], l_ + 8192); } while (0)
; #define VDMA(k0, b) do { const char* g_ = (const char*)(Vh + (long)(k0) * DM); char* l_ = V_lds + (b) * 32768 + wu * 1024; \
;     DMA16(g_ + voff[0], l_); DMA16(g_ + voff[1], l_ + 8192); DMA16(g_ + voff[0] + 256, l_ + 16384); DMA16(g_ + voff[1] + 256, l_ + 16384 + 8192); } while (0)
; #define DMAWAIT() asm volatile("s_waitcnt vmcnt(0)" ::: "memory")
; #define QKH(b) do { S = f32x16{}; const char* Ks_ = K_lds + (b) * 16384; _Pragma("unroll") for (int d0 = 0; d0 < 8; ++d0) { \
;     const bf16x8 kf = *reinterpret_cast<const bf16x8*>(Ks_ + KSWZ(32 * kh + r32, (d0 * 16 + hi * 8) * 2)); \
;     S = __builtin_amdgcn_mfma_f32_32x32x16_bf16(kf, qr[d0], S, 0, 0, 0); } } while (0)
; #define SMX_FIN(pbuf) do { _Pragma("unroll") for (int r = 0; r < 16; ++r) l_reg += S[r]; \
;     PK4S(0, po0); PK4S(8, po1); \
;     *(bf16x8*)(pw + (pbuf) * 16384) = po0; *(bf16x8*)(pw + (pbuf) * 16384 + 16) = po1; } while (0)
; template <int PROBE, int MODE>
; DI void dattn_body(const u16* __restrict__ Qb, const u16* __restrict__ Kh, const u16* __restrict__ Vh, u16* __restrict__ Ob, const u16* __restrict__ O1, float lam, const float* __restrict__ subg, int seq, int q0, float kmax2, char* lds) {
;     ...
;   f32x16 o[4] = {}; f32x16 S; float l_reg = 0.f; bf16x8 po0, po1; const int NT = seq / KVBLK;
;   KDMA(0, 0); VDMA(0, 0); KDMA(KVBLK, 1);
;   DMAWAIT();
;   __syncthreads();
;   const float biasL = __uint_as_float(__builtin_amdgcn_readfirstlane(__float_as_uint(tab[0]))), biasR = __uint_as_float(__builtin_amdgcn_readfirstlane(__float_as_uint(tab[256])));
;   const float Mrow = C * __builtin_sqrtf(q2 * kmax2) + tab[257];
;   QKH(0);
;   { SMX_SETUP(0) SMX_CH(0); SMX_CH(1); SMX_CH(2); SMX_CH(3); SMX_FIN(0); }
	ds_read_b32 v2, v2
	v_readlane_b32 s0, v255, 10
	v_mul_f32_e32 v1, 0x4f800000, v0
	s_add_i32 s35, s87, 0xff
	s_cmpk_gt_u32 s35, 0x1be
	s_waitcnt lgkmcnt(0)
	v_readfirstlane_b32 s20, v2
	v_mov_b32_e32 v2, s0
	s_mov_b32 s0, 0xf800000
	v_cmp_gt_f32_e32 vcc, s0, v0
	ds_read_b64 v[18:19], v2
	s_waitcnt lgkmcnt(0)
	v_readfirstlane_b32 s21, v18
	v_cndmask_b32_e32 v0, v0, v1, vcc
	v_sqrt_f32_e32 v1, v0
	v_mov_b32_e32 v158, v19
	v_add_u32_e32 v2, -1, v1
	v_fma_f32 v3, -v2, v1, v0
	v_cmp_ge_f32_e64 s[0:1], 0, v3
	v_add_u32_e32 v3, 1, v1
	s_nop 0
	v_cndmask_b32_e64 v2, v1, v2, s[0:1]
	v_fma_f32 v1, -v3, v1, v0
	v_cmp_lt_f32_e64 s[0:1], 0, v1
	s_nop 1
	v_cndmask_b32_e64 v1, v2, v3, s[0:1]
	v_mul_f32_e32 v2, 0x37800000, v1
	v_cndmask_b32_e32 v1, v1, v2, vcc
	v_cmp_class_f32_e32 vcc, v0, v219
	s_movk_i32 s0, 0x70
	v_bitop3_b32 v198, v16, v195, s0 bitop3:0x78
	v_cndmask_b32_e32 v18, v1, v0, vcc
	v_lshlrev_b32_e32 v0, 13, v196
	v_lshlrev_b32_e32 v1, 8, v192
	v_add3_u32 v21, s95, v0, v1
	v_add_u32_e32 v0, v21, v198
	ds_read_b128 v[0:3], v0
	v_add_u32_e32 v23, v21, v199
	ds_read_b128 v[26:29], v23
	s_waitcnt lgkmcnt(1)
	v_mfma_f32_32x32x16_bf16 v[0:15], v[0:3], v[82:85], 0
	v_add_u32_e32 v23, v21, v200
	s_movk_i32 s0, 0x60
	v_bitop3_b32 v201, v16, v20, s0 bitop3:0x36
	s_movk_i32 s0, 0xa0
	v_bitop3_b32 v203, v16, v20, s0 bitop3:0x36
	s_movk_i32 s0, 0xc0
	v_bitop3_b32 v204, v16, v20, s0 bitop3:0x36
	s_waitcnt lgkmcnt(0)
	v_mfma_f32_32x32x16_bf16 v[0:15], v[26:29], v[86:89], v[0:15]
	ds_read_b128 v[26:29], v23
	v_add_u32_e32 v23, v21, v201
	s_movk_i32 s0, 0xe0
	v_bitop3_b32 v205, v16, v20, s0 bitop3:0x36
	v_add_u32_e32 v16, v21, v205
	s_cselect_b64 s[0:1], -1, 0
	s_cmp_lt_i32 s18, 0
	s_waitcnt lgkmcnt(0)
	v_mfma_f32_32x32x16_bf16 v[0:15], v[26:29], v[90:93], v[0:15]
	ds_read_b128 v[26:29], v23
	v_add_u32_e32 v23, v21, v202
	v_fmac_f32_e32 v158, 0x3e0293ee, v18
	s_cselect_b64 s[44:45], -1, 0
	v_mov_b32_e32 v18, s21
	s_cmpk_lt_u32 s35, 0x1bf
	s_mov_b64 s[18:19], -1
	s_waitcnt lgkmcnt(0)
	v_mfma_f32_32x32x16_bf16 v[0:15], v[26:29], v[94:97], v[0:15]
	ds_read_b128 v[26:29], v23
	v_add_u32_e32 v23, v21, v203
	s_waitcnt lgkmcnt(0)
	v_mfma_f32_32x32x16_bf16 v[0:15], v[26:29], v[98:101], v[0:15]
	ds_read_b128 v[26:29], v23
	v_add_u32_e32 v23, v21, v204
	s_waitcnt lgkmcnt(0)
	v_mfma_f32_32x32x16_bf16 v[0:15], v[26:29], v[102:105], v[0:15]
	ds_read_b128 v[26:29], v23
	s_waitcnt lgkmcnt(0)
	v_mfma_f32_32x32x16_bf16 v[0:15], v[26:29], v[106:109], v[0:15]
	ds_read_b128 v[26:29], v16
	v_mov_b32_e32 v16, s20
	v_cndmask_b32_e64 v16, v16, v18, s[44:45]
	v_sub_f32_e32 v16, v16, v158
	s_waitcnt lgkmcnt(0)
	v_mfma_f32_32x32x16_bf16 v[0:15], v[26:29], v[110:113], v[0:15]
	s_cbranch_scc1 .LBB0_231
	s_nop 10
	v_pk_fma_f32 v[18:19], v[0:1], s[12:13], v[16:17] op_sel_hi:[1,0,0]
	v_pk_fma_f32 v[20:21], v[2:3], s[12:13], v[16:17] op_sel_hi:[1,0,0]
	s_mov_b64 s[18:19], 0

; #define SBAR() __builtin_amdgcn_sched_barrier(0)
; #define DMAWAIT() asm volatile("s_waitcnt vmcnt(0)" ::: "memory")
; #define SMX_FIN(pbuf) do { _Pragma("unroll") for (int r = 0; r < 16; ++r) l_reg += S[r]; \
;     PK4S(0, po0); PK4S(8, po1); \
;     *(bf16x8*)(pw + (pbuf) * 16384) = po0; *(bf16x8*)(pw + (pbuf) * 16384 + 16) = po1; } while (0)
; #define VRD(D0, X) do { X##0 = tr_read<v_rd_off(D0, 0, 0)>(vb); X##1 = tr_read<v_rd_off(D0, 0, 1)>(vb); X##2 = tr_read<v_rd_off(D0, 1, 0)>(vb); X##3 = tr_read<v_rd_off(D0, 1, 1)>(vb); \
;     X##4 = tr_read<v_rd_off(D0, 2, 0)>(vb); X##5 = tr_read<v_rd_off(D0, 2, 1)>(vb); X##6 = tr_read<v_rd_off(D0, 3, 0)>(vb); X##7 = tr_read<v_rd_off(D0, 3, 1)>(vb); } while (0)
; #define LWAIT() do { asm volatile("s_waitcnt lgkmcnt(0)" ::: "memory"); SBAR(); } while (0)
; #define VMMP(D0, X) do { if (!(PROBE & 8)) VMM(D0, X); } while (0)
; template <int PROBE, int MODE>
; DI void dattn_body(const u16* __restrict__ Qb, const u16* __restrict__ Kh, const u16* __restrict__ Vh, u16* __restrict__ Ob, const u16* __restrict__ O1, float lam, const float* __restrict__ subg, int seq, int q0, float kmax2, char* lds) {
;     ...
;     const bf16x8 pb0 = *(const bf16x8*)(pr + (j & 1) * 16384), pb1 = *(const bf16x8*)(pr + (j & 1) * 16384 + 16);
;     const int vb = vb0 + (j & 1) * 32768;
;     s16x4 va0, va1, va2, va3, va4, va5, va6, va7, vc0, vc1, vc2, vc3, vc4, vc5, vc6, vc7;
;     VRD(0, va);
;     if (more) { asm volatile("s_waitcnt lgkmcnt(10)" ::: "memory"); SBAR();
;       if (!(PROBE & 4)) { S = f32x16{};
; #pragma unroll
;       for (int d0 = 0; d0 < 8; ++d0) S = __builtin_amdgcn_mfma_f32_32x32x16_bf16(kf[d0], qr[d0], S, 0, 0, 0); }
;       SBAR(); }
;     const bf16x8 A0 = kh ? pb0 : po0, A1 = kh ? pb1 : po1, A2 = kh ? po0 : pb0, A3 = kh ? po1 : pb1;
;     SMX_SETUP(j + 1)
;     ...
;     LWAIT(); VRD(1, vc); VMMP(0, va); SMXP(0);
;     LWAIT(); VRD(2, va); VMMP(1, vc); SMXP(1);
;     LWAIT(); VRD(3, vc); VMMP(2, va); SMXP(2);
;     LWAIT(); VMMP(3, vc); SMXP(3);
;     if (!(PROBE & 2)) { if (more) SMX_FIN((j + 1) & 1); }
;     DMAWAIT();
;     __syncthreads();
;     ...
;   }
;   { auto rr = __builtin_amdgcn_permlane32_swap(__float_as_uint(l_reg), __float_as_uint(l_reg), false, false); l_reg = __uint_as_float(rr[0]) + __uint_as_float(rr[1]); }
;   if (hi == 0) lsum[wid * 32 + r32] = l_reg;
;   __syncthreads();
.LBB0_265:
	s_and_b32 s18, s83, 1
	s_lshl_b32 s75, s18, 14
	v_add_u32_e32 v68, s75, v210
	s_lshl_b32 s85, s18, 15
	ds_read_b128 v[64:67], v68
	ds_read_b128 v[68:71], v68 offset:16
	v_add_u32_e32 v102, s85, v212
	ds_read_b64_tr_b16 v[72:73], v102 offset:0
	ds_read_b64_tr_b16 v[74:75], v102 offset:0x800
	ds_read_b64_tr_b16 v[76:77], v102 offset:0x1000
	ds_read_b64_tr_b16 v[78:79], v102 offset:0x1800
	ds_read_b64_tr_b16 v[82:83], v102 offset:0x2000
	ds_read_b64_tr_b16 v[84:85], v102 offset:0x2800
	ds_read_b64_tr_b16 v[86:87], v102 offset:0x3000
	ds_read_b64_tr_b16 v[88:89], v102 offset:0x3800
	s_waitcnt lgkmcnt(0)
	s_waitcnt lgkmcnt(1)
	v_cndmask_b32_e64 v91, v65, v115, s[46:47]
	v_cndmask_b32_e64 v90, v64, v114, s[46:47]
	v_cndmask_b32_e64 v65, v115, v65, s[46:47]
	v_cndmask_b32_e64 v64, v114, v64, s[46:47]
	v_cndmask_b32_e64 v93, v67, v117, s[46:47]
	v_cndmask_b32_e64 v92, v66, v116, s[46:47]
	s_waitcnt lgkmcnt(0)
	v_cndmask_b32_e64 v97, v71, v133, s[46:47]
	v_cndmask_b32_e64 v96, v70, v132, s[46:47]
	v_cndmask_b32_e64 v95, v69, v131, s[46:47]
	v_cndmask_b32_e64 v94, v68, v130, s[46:47]
	v_cndmask_b32_e64 v67, v117, v67, s[46:47]
	v_cndmask_b32_e64 v66, v116, v66, s[46:47]
	v_cndmask_b32_e64 v71, v133, v71, s[46:47]
	v_cndmask_b32_e64 v70, v132, v70, s[46:47]
	v_cndmask_b32_e64 v69, v131, v69, s[46:47]
	v_cndmask_b32_e64 v68, v130, v68, s[46:47]
	v_mfma_f32_32x32x16_bf16 v[0:15], v[90:93], v[72:75], v[0:15]
	ds_read_b64_tr_b16 v[72:73], v102 offset:0x200
	ds_read_b64_tr_b16 v[74:75], v102 offset:0xa00
	v_mfma_f32_32x32x16_bf16 v[0:15], v[94:97], v[76:79], v[0:15]
	ds_read_b64_tr_b16 v[76:77], v102 offset:0x1200
	ds_read_b64_tr_b16 v[78:79], v102 offset:0x1a00
	v_mfma_f32_32x32x16_bf16 v[0:15], v[64:67], v[82:85], v[0:15]
	ds_read_b64_tr_b16 v[82:83], v102 offset:0x2200
	ds_read_b64_tr_b16 v[84:85], v102 offset:0x2a00
	ds_read_b64_tr_b16 v[98:99], v102 offset:0x3200
	ds_read_b64_tr_b16 v[100:101], v102 offset:0x3a00
	s_waitcnt lgkmcnt(0)
	v_mfma_f32_32x32x16_bf16 v[0:15], v[68:71], v[86:89], v[0:15]
	v_mfma_f32_32x32x16_bf16 v[16:31], v[90:93], v[72:75], v[16:31]
	ds_read_b64_tr_b16 v[72:73], v102 offset:0x400
	ds_read_b64_tr_b16 v[74:75], v102 offset:0xc00
	v_mfma_f32_32x32x16_bf16 v[16:31], v[94:97], v[76:79], v[16:31]
	ds_read_b64_tr_b16 v[76:77], v102 offset:0x1400
	ds_read_b64_tr_b16 v[78:79], v102 offset:0x1c00
	v_mfma_f32_32x32x16_bf16 v[16:31], v[64:67], v[82:85], v[16:31]
	ds_read_b64_tr_b16 v[82:83], v102 offset:0x2400
	ds_read_b64_tr_b16 v[84:85], v102 offset:0x2c00
	ds_read_b64_tr_b16 v[86:87], v102 offset:0x3400
	ds_read_b64_tr_b16 v[88:89], v102 offset:0x3c00
	s_waitcnt lgkmcnt(0)
	v_mfma_f32_32x32x16_bf16 v[16:31], v[68:71], v[98:101], v[16:31]
	v_mfma_f32_32x32x16_bf16 v[32:47], v[90:93], v[72:75], v[32:47]
	ds_read_b64_tr_b16 v[72:73], v102 offset:0x600
	ds_read_b64_tr_b16 v[74:75], v102 offset:0xe00
	v_mfma_f32_32x32x16_bf16 v[32:47], v[94:97], v[76:79], v[32:47]
	ds_read_b64_tr_b16 v[76:77], v102 offset:0x1600
	ds_read_b64_tr_b16 v[78:79], v102 offset:0x1e00
	v_mfma_f32_32x32x16_bf16 v[32:47], v[64:67], v[82:85], v[32:47]
	ds_read_b64_tr_b16 v[82:83], v102 offset:0x2600
	ds_read_b64_tr_b16 v[84:85], v102 offset:0x2e00
	ds_read_b64_tr_b16 v[98:99], v102 offset:0x3600
	ds_read_b64_tr_b16 v[100:101], v102 offset:0x3e00
	s_waitcnt lgkmcnt(0)
	v_mfma_f32_32x32x16_bf16 v[32:47], v[68:71], v[86:89], v[32:47]
	v_mfma_f32_32x32x16_bf16 v[48:63], v[90:93], v[72:75], v[48:63]
	s_waitcnt vmcnt(0)
	v_cmp_gt_u32_e32 vcc, 32, v193
	s_barrier
	v_mfma_f32_32x32x16_bf16 v[48:63], v[94:97], v[76:79], v[48:63]
	v_mfma_f32_32x32x16_bf16 v[48:63], v[64:67], v[82:85], v[48:63]
	v_mov_b32_e32 v65, v209
	s_nop 1
	v_permlane32_swap_b32_e32 v209, v65
	v_lshlrev_b32_e32 v64, 7, v194
	v_mfma_f32_32x32x16_bf16 v[48:63], v[68:71], v[98:101], v[48:63]
	s_and_saveexec_b64 s[18:19], vcc
	s_add_i32 s20, 16, 0x20000
	v_lshlrev_b32_e32 v66, 2, v192
	v_add3_u32 v66, s20, v64, v66
	v_add_f32_e32 v65, v209, v65
	ds_write_b32 v66, v65
	s_or_b64 exec, exec, s[18:19]
	s_lshl_b64 s[46:47], s[0:1], 1
	v_readlane_b32 s0, v251, 41
	v_readlane_b32 s1, v251, 42
	s_add_u32 s0, s0, s46
	s_addc_u32 s1, s1, s47
	s_lshl_b32 s74, s24, 1
	s_add_u32 s48, s0, s74
	s_addc_u32 s49, s1, 0
	s_add_i32 s82, 16, 0x20000
	v_add_u32_e32 v82, s82, v64
	v_lshl_add_u32 v83, v208, 7, s82
	v_lshlrev_b32_e32 v72, 2, v206
	v_add_u32_e32 v84, v82, v72
	v_add_u32_e32 v85, v83, v72
	s_waitcnt lgkmcnt(0)
	s_barrier
; DI int crow(int r, int hi) { return (r & 3) + 8 * (r >> 2) + 4 * hi; }
; DI u16 f2bf(float x) { return (u16)(cvtpk(x, x) & 0xffffu); }
; template <int PROBE, int MODE>
; DI void dattn_body(const u16* __restrict__ Qb, const u16* __restrict__ Kh, const u16* __restrict__ Vh, u16* __restrict__ Ob, const u16* __restrict__ O1, float lam, const float* __restrict__ subg, int seq, int q0, float kmax2, char* lds) {
;     ...
;   float rli[16];
; #pragma unroll
;   for (int r = 0; r < 16; ++r) rli[r] = __builtin_amdgcn_rcpf(lsum[wid * 32 + crow(r, hi)] + lsum[(wid ^ 1) * 32 + crow(r, hi)]);
;   u16* Ow = Ob + (long)(rg * 32) * 4096 + kh * 128;
;   if (PROBE) {
;     float acc_ = 0.f;
; #pragma unroll
;     for (int r = 0; r < 16; ++r)
; #pragma unroll
;       for (int d0 = 0; d0 < 4; ++d0) acc_ += o[d0][r] * rli[r];
;     if (acc_ == 123.456f && seq < 0) Ow[0] = f2bf(acc_);
;     return;
;   }
;   (void)Ow;
;   {
;     char* Ot = lds;
;     constexpr int UOROW = 528;
; #pragma unroll
;     for (int r = 0; r < 16; ++r) { const int orow = rg * 32 + crow(r, hi);
; #pragma unroll
;       for (int d0 = 0; d0 < 4; ++d0) *reinterpret_cast<u16*>(Ot + orow * UOROW + (kh * 128 + d0 * 32 + r32) * 2) = f2bf(o[d0][r] * rli[r]); }
	ds_read_b128 v[64:67], v84
	ds_read_b128 v[68:71], v84 offset:32
	ds_read_b128 v[72:75], v85
	ds_read_b128 v[76:79], v85 offset:32
	v_and_b32_e32 v176, 0x1f0, v195
	s_mov_b32 s0, 0x10000
	v_mov_b32_e32 v155, v177
	s_waitcnt lgkmcnt(1)
	v_add_f32_e32 v64, v64, v72
	v_rcp_f32_e32 v72, v64
	v_add_f32_e32 v64, v65, v73
	v_rcp_f32_e32 v73, v64
	v_add_f32_e32 v64, v66, v74
	v_rcp_f32_e32 v74, v64
	v_add_f32_e32 v64, v67, v75
	v_rcp_f32_e32 v75, v64
	s_waitcnt lgkmcnt(0)
	v_add_f32_e32 v64, v68, v76
	v_rcp_f32_e32 v76, v64
	v_add_f32_e32 v64, v69, v77
	v_rcp_f32_e32 v77, v64
	v_add_f32_e32 v64, v70, v78
	v_rcp_f32_e32 v78, v64
	v_add_f32_e32 v64, v71, v79
	v_rcp_f32_e32 v79, v64
	ds_read_b128 v[64:67], v84 offset:64
	ds_read_b128 v[68:71], v85 offset:64
	v_mul_f32_e32 v0, v0, v72
	v_mov_b32_e32 v153, v177
	v_mov_b32_e32 v157, v177
	v_readlane_b32 s55, v255, 34
	s_waitcnt lgkmcnt(0)
	v_add_f32_e32 v64, v64, v68
	v_rcp_f32_e32 v68, v64
	v_add_f32_e32 v64, v65, v69
	v_rcp_f32_e32 v69, v64
	v_add_f32_e32 v64, v66, v70
	v_rcp_f32_e32 v70, v64
	v_add_f32_e32 v64, v67, v71
	v_rcp_f32_e32 v71, v64
	v_lshlrev_b32_e32 v64, 2, v207
	v_add_u32_e32 v65, v82, v64
	v_add_u32_e32 v64, v83, v64
	ds_read_b32 v65, v65
	ds_read_b32 v64, v64
	v_lshlrev_b32_e32 v83, 8, v196
	s_waitcnt lgkmcnt(0)
	v_add_f32_e32 v64, v65, v64
	v_rcp_f32_e32 v82, v64
	ds_read2_b32 v[64:65], v84 offset0:25 offset1:26
	ds_read2_b32 v[66:67], v85 offset0:25 offset1:26
	s_waitcnt lgkmcnt(0)
	v_add_f32_e32 v64, v64, v66
	v_rcp_f32_e32 v66, v64
	v_add_f32_e32 v64, v65, v67
	ds_read_b32 v65, v84 offset:108
	ds_read_b32 v67, v85 offset:108
	v_lshlrev_b32_e32 v84, 1, v192
	v_cvt_pk_bf16_f32 v0, v0, v0
	v_rcp_f32_e32 v64, v64
	s_waitcnt lgkmcnt(0)
	v_add_f32_e32 v65, v65, v67
	v_add_u32_e32 v67, v206, v197
	v_mul_lo_u32 v67, v67, s28
	v_add_u32_e32 v67, 16, v67
	v_add3_u32 v67, v67, v83, v84
	ds_write_b16 v67, v0
	v_mul_f32_e32 v0, v16, v72
	v_cvt_pk_bf16_f32 v0, v0, v0
	ds_write_b16 v67, v0 offset:64
	v_mul_f32_e32 v0, v32, v72
	v_cvt_pk_bf16_f32 v0, v0, v0
	ds_write_b16 v67, v0 offset:128
	v_mul_f32_e32 v0, v48, v72
	v_cvt_pk_bf16_f32 v0, v0, v0
	ds_write_b16 v67, v0 offset:192
	v_mul_f32_e32 v0, v1, v73
	v_cvt_pk_bf16_f32 v0, v0, v0
	ds_write_b16 v67, v0 offset:528
	v_mul_f32_e32 v0, v17, v73
	v_cvt_pk_bf16_f32 v0, v0, v0
	ds_write_b16 v67, v0 offset:592
	v_mul_f32_e32 v0, v33, v73
	v_cvt_pk_bf16_f32 v0, v0, v0
	ds_write_b16 v67, v0 offset:656
	v_mul_f32_e32 v0, v49, v73
	v_cvt_pk_bf16_f32 v0, v0, v0
	ds_write_b16 v67, v0 offset:720
	v_mul_f32_e32 v0, v2, v74
	v_cvt_pk_bf16_f32 v0, v0, v0
	ds_write_b16 v67, v0 offset:1056
	v_mul_f32_e32 v0, v18, v74
	v_cvt_pk_bf16_f32 v0, v0, v0
	ds_write_b16 v67, v0 offset:1120
	v_mul_f32_e32 v0, v34, v74
	v_cvt_pk_bf16_f32 v0, v0, v0
	ds_write_b16 v67, v0 offset:1184
	v_mul_f32_e32 v0, v50, v74
	v_cvt_pk_bf16_f32 v0, v0, v0
	ds_write_b16 v67, v0 offset:1248
	v_mul_f32_e32 v0, v3, v75
	v_cvt_pk_bf16_f32 v0, v0, v0
	ds_write_b16 v67, v0 offset:1584
	v_mul_f32_e32 v0, v19, v75
	v_cvt_pk_bf16_f32 v0, v0, v0
	ds_write_b16 v67, v0 offset:1648
	v_mul_f32_e32 v0, v35, v75
	v_cvt_pk_bf16_f32 v0, v0, v0
	ds_write_b16 v67, v0 offset:1712
	v_mul_f32_e32 v0, v51, v75
	v_cvt_pk_bf16_f32 v0, v0, v0
	ds_write_b16 v67, v0 offset:1776
	v_mul_f32_e32 v0, v4, v76
	v_cvt_pk_bf16_f32 v0, v0, v0
	ds_write_b16 v67, v0 offset:4224
	v_mul_f32_e32 v0, v20, v76
	v_cvt_pk_bf16_f32 v0, v0, v0
	ds_write_b16 v67, v0 offset:4288
	v_mul_f32_e32 v0, v36, v76
	v_cvt_pk_bf16_f32 v0, v0, v0
	ds_write_b16 v67, v0 offset:4352
	v_mul_f32_e32 v0, v52, v76
	v_cvt_pk_bf16_f32 v0, v0, v0
	ds_write_b16 v67, v0 offset:4416
	v_mul_f32_e32 v0, v5, v77
	v_cvt_pk_bf16_f32 v0, v0, v0
	ds_write_b16 v67, v0 offset:4752
	v_mul_f32_e32 v0, v21, v77
	v_cvt_pk_bf16_f32 v0, v0, v0
	ds_write_b16 v67, v0 offset:4816
	v_mul_f32_e32 v0, v37, v77
	v_cvt_pk_bf16_f32 v0, v0, v0
	ds_write_b16 v67, v0 offset:4880
	v_mul_f32_e32 v0, v53, v77
	v_cvt_pk_bf16_f32 v0, v0, v0
	ds_write_b16 v67, v0 offset:4944
	v_mul_f32_e32 v0, v6, v78
	v_cvt_pk_bf16_f32 v0, v0, v0
	ds_write_b16 v67, v0 offset:5280
	v_mul_f32_e32 v0, v22, v78
	v_cvt_pk_bf16_f32 v0, v0, v0
	ds_write_b16 v67, v0 offset:5344
	v_mul_f32_e32 v0, v38, v78
	v_cvt_pk_bf16_f32 v0, v0, v0
	ds_write_b16 v67, v0 offset:5408
	v_mul_f32_e32 v0, v54, v78
	v_cvt_pk_bf16_f32 v0, v0, v0
	ds_write_b16 v67, v0 offset:5472
	v_mul_f32_e32 v0, v7, v79
	v_cvt_pk_bf16_f32 v0, v0, v0
	ds_write_b16 v67, v0 offset:5808
	v_mul_f32_e32 v0, v23, v79
	v_cvt_pk_bf16_f32 v0, v0, v0
	ds_write_b16 v67, v0 offset:5872
	v_mul_f32_e32 v0, v39, v79
	v_cvt_pk_bf16_f32 v0, v0, v0
	ds_write_b16 v67, v0 offset:5936
	v_mul_f32_e32 v0, v55, v79
	v_cvt_pk_bf16_f32 v0, v0, v0
	ds_write_b16 v67, v0 offset:6000
	v_mul_f32_e32 v0, v8, v68
	v_cvt_pk_bf16_f32 v0, v0, v0
	ds_write_b16 v67, v0 offset:8448
	v_mul_f32_e32 v0, v24, v68
	v_cvt_pk_bf16_f32 v0, v0, v0
	ds_write_b16 v67, v0 offset:8512
	v_mul_f32_e32 v0, v40, v68
	v_cvt_pk_bf16_f32 v0, v0, v0
	ds_write_b16 v67, v0 offset:8576
	v_mul_f32_e32 v0, v56, v68
	v_cvt_pk_bf16_f32 v0, v0, v0
	ds_write_b16 v67, v0 offset:8640
	v_mul_f32_e32 v0, v9, v69
	v_cvt_pk_bf16_f32 v0, v0, v0
	ds_write_b16 v67, v0 offset:8976
	v_mul_f32_e32 v0, v25, v69
	v_cvt_pk_bf16_f32 v0, v0, v0
	ds_write_b16 v67, v0 offset:9040
	v_mul_f32_e32 v0, v41, v69
	v_cvt_pk_bf16_f32 v0, v0, v0
	ds_write_b16 v67, v0 offset:9104
	v_mul_f32_e32 v0, v57, v69
	v_cvt_pk_bf16_f32 v0, v0, v0
	ds_write_b16 v67, v0 offset:9168
	v_mul_f32_e32 v0, v10, v70
	v_cvt_pk_bf16_f32 v0, v0, v0
	ds_write_b16 v67, v0 offset:9504
	v_mul_f32_e32 v0, v26, v70
	v_cvt_pk_bf16_f32 v0, v0, v0
	ds_write_b16 v67, v0 offset:9568
; DI int crow(int r, int hi) { return (r & 3) + 8 * (r >> 2) + 4 * hi; }
; DI u16 f2bf(float x) { return (u16)(cvtpk(x, x) & 0xffffu); }
; template <int PROBE, int MODE>
; DI void dattn_body(const u16* __restrict__ Qb, const u16* __restrict__ Kh, const u16* __restrict__ Vh, u16* __restrict__ Ob, const u16* __restrict__ O1, float lam, const float* __restrict__ subg, int seq, int q0, float kmax2, char* lds) {
;     ...
;   const u16* Qw = Qb + (long)(rg * 32 + r32) * DM + hi * 8;
; #pragma unroll
;   for (int d0 = 0; d0 < 8; ++d0) qr[d0] = ld8(Qw + d0 * 16);
;   float q2 = 0.f;
; #pragma unroll
;   for (int d0 = 0; d0 < 8; ++d0)
; #pragma unroll
;     for (int e = 0; e < 8; ++e) { const float f = bf2f((u16)qr[d0][e]); q2 = fmaf(f, f, q2); }
;   { auto rr = __builtin_amdgcn_permlane32_swap(__float_as_uint(q2), __float_as_uint(q2), false, false); q2 = __uint_as_float(rr[0]) + __uint_as_float(rr[1]); }
;   const int sr = tid >> 4, sc = (tid & 15) * 8, vst0 = v_st(sr, sc), vst1 = v_st(32 + sr, sc), kst0 = KSWZ(sr, sc * 2), kst1 = KSWZ(32 + sr, sc * 2);
;   const int vb0 = (int)(uintptr_t)V_lds + kh * 16384 + v_rd_base(lane);
;   const int qpos = q0 + rg * 32 + r32;
;   char* pw = P_lds + wid * 2048 + lane * 32;
;   const char* pr = P_lds + (wid ^ 1) * 2048 + lane * 32;
;   const int wu = __builtin_amdgcn_readfirstlane(wid);
;   unsigned koff[2], voff[2];
; #pragma unroll
;   for (int i = 0; i < 2; ++i) {
;     const int a = i * 8192 + wid * 1024 + lane * 16;
;     { const int row = a >> 8, pch = (a & 255) >> 4, c = pch ^ (row & 7); koff[i] = (unsigned)(row * DM + c * 8) * 2u; }
;     { const int q = a >> 4, sub = q >> 5, kk = (sub >> 2) * 8 + ((q & 31) >> 2), k = (kk & ~0xC) | ((kk & 4) << 1) | ((kk & 8) >> 1), col = (sub & 3) * 32 + (q & 3) * 8;
;       voff[i] = (unsigned)(k * DM + col) * 2u; }
;     ...
;     for (int r = 0; r < 16; ++r) { const int orow = rg * 32 + crow(r, hi);
; #pragma unroll
;       for (int d0 = 0; d0 < 4; ++d0) *reinterpret_cast<u16*>(Ot + orow * UOROW + (kh * 128 + d0 * 32 + r32) * 2) = f2bf(o[d0][r] * rli[r]); }
;     __syncthreads();
;     if (MODE == 0) {
; #pragma unroll
;       for (int it = 0; it < 8; ++it) {
;         const int row = (tid >> 5) + 16 * it, c8 = (tid & 31) * 8;
;         *reinterpret_cast<bf16x8*>(Ob + (long)row * DM + c8) = *reinterpret_cast<const bf16x8*>(Ot + row * UOROW + c8 * 2);
	v_mul_f32_e32 v0, v42, v70
	v_cvt_pk_bf16_f32 v0, v0, v0
	ds_write_b16 v67, v0 offset:9632
	v_mul_f32_e32 v0, v58, v70
	v_cvt_pk_bf16_f32 v0, v0, v0
	ds_write_b16 v67, v0 offset:9696
	v_mul_f32_e32 v0, v11, v71
	v_cvt_pk_bf16_f32 v0, v0, v0
	ds_write_b16 v67, v0 offset:10032
	v_mul_f32_e32 v0, v27, v71
	v_cvt_pk_bf16_f32 v0, v0, v0
	ds_write_b16 v67, v0 offset:10096
	v_mul_f32_e32 v0, v43, v71
	v_cvt_pk_bf16_f32 v0, v0, v0
	ds_write_b16 v67, v0 offset:10160
	v_mul_f32_e32 v0, v59, v71
	v_cvt_pk_bf16_f32 v0, v0, v0
	ds_write_b16 v67, v0 offset:10224
	v_mul_f32_e32 v0, v12, v82
	v_cvt_pk_bf16_f32 v0, v0, v0
	ds_write_b16 v67, v0 offset:12672
	v_mul_f32_e32 v0, v28, v82
	v_cvt_pk_bf16_f32 v0, v0, v0
	ds_write_b16 v67, v0 offset:12736
	v_mul_f32_e32 v0, v44, v82
	v_cvt_pk_bf16_f32 v0, v0, v0
	ds_write_b16 v67, v0 offset:12800
	v_mul_f32_e32 v0, v60, v82
	v_cvt_pk_bf16_f32 v0, v0, v0
	ds_write_b16 v67, v0 offset:12864
	v_mul_f32_e32 v0, v13, v66
	v_cvt_pk_bf16_f32 v0, v0, v0
	ds_write_b16 v67, v0 offset:13200
	v_mul_f32_e32 v0, v29, v66
	v_cvt_pk_bf16_f32 v0, v0, v0
	ds_write_b16 v67, v0 offset:13264
	v_mul_f32_e32 v0, v45, v66
	v_cvt_pk_bf16_f32 v0, v0, v0
	ds_write_b16 v67, v0 offset:13328
	v_mul_f32_e32 v0, v61, v66
	v_cvt_pk_bf16_f32 v0, v0, v0
	ds_write_b16 v67, v0 offset:13392
	v_mul_f32_e32 v0, v14, v64
	v_cvt_pk_bf16_f32 v0, v0, v0
	ds_write_b16 v67, v0 offset:13728
	v_mul_f32_e32 v0, v30, v64
	v_cvt_pk_bf16_f32 v0, v0, v0
	v_rcp_f32_e32 v65, v65
	ds_write_b16 v67, v0 offset:13792
	v_mul_f32_e32 v0, v46, v64
	v_cvt_pk_bf16_f32 v0, v0, v0
	ds_write_b16 v67, v0 offset:13856
	v_mul_f32_e32 v0, v62, v64
	v_cvt_pk_bf16_f32 v0, v0, v0
	ds_write_b16 v67, v0 offset:13920
	v_mul_f32_e32 v0, v15, v65
	v_cvt_pk_bf16_f32 v0, v0, v0
	ds_write_b16 v67, v0 offset:14256
	v_mul_f32_e32 v0, v31, v65
	v_cvt_pk_bf16_f32 v0, v0, v0
	ds_write_b16 v67, v0 offset:14320
	v_mul_f32_e32 v0, v47, v65
	v_cvt_pk_bf16_f32 v0, v0, v0
	ds_write_b16 v67, v0 offset:14384
	v_mul_f32_e32 v0, v63, v65
	v_cvt_pk_bf16_f32 v0, v0, v0
	v_ashrrev_i32_e32 v4, 5, v175
	ds_write_b16 v67, v0 offset:14448
	v_mul_lo_u32 v0, v4, s28
	v_add3_u32 v8, 16, v176, v0
	s_waitcnt lgkmcnt(0)
	s_barrier
	ds_read_b128 v[0:3], v8
	v_ashrrev_i32_e32 v5, 31, v4
	v_lshl_add_u64 v[6:7], s[48:49], 0, v[176:177]
	v_lshlrev_b64 v[4:5], 12, v[4:5]
	v_lshl_add_u64 v[4:5], v[6:7], 0, v[4:5]
	s_waitcnt lgkmcnt(0)
	global_store_dwordx4 v[4:5], v[0:3], off
	ds_read_b128 v[0:3], v8 offset:8448
	v_add_co_u32_e32 v6, vcc, s0, v4
	s_mov_b32 s0, 0x20000
	s_nop 0
	v_addc_co_u32_e32 v7, vcc, 0, v5, vcc
	s_waitcnt lgkmcnt(0)
	global_store_dwordx4 v[6:7], v[0:3], off
	ds_read_b128 v[0:3], v8 offset:16896
	v_add_co_u32_e32 v6, vcc, s0, v4
	s_mov_b32 s0, 0x30000
	s_nop 0
	v_addc_co_u32_e32 v7, vcc, 0, v5, vcc
	s_waitcnt lgkmcnt(0)
	global_store_dwordx4 v[6:7], v[0:3], off
	ds_read_b128 v[0:3], v8 offset:25344
	v_add_co_u32_e32 v6, vcc, s0, v4
	s_mov_b32 s0, 0x40000
	s_nop 0
	v_addc_co_u32_e32 v7, vcc, 0, v5, vcc
	s_waitcnt lgkmcnt(0)
	global_store_dwordx4 v[6:7], v[0:3], off
	ds_read_b128 v[0:3], v8 offset:33792
	v_add_co_u32_e32 v6, vcc, s0, v4
	s_mov_b32 s0, 0x50000
	s_nop 0
	v_addc_co_u32_e32 v7, vcc, 0, v5, vcc
	s_waitcnt lgkmcnt(0)
	global_store_dwordx4 v[6:7], v[0:3], off
	ds_read_b128 v[0:3], v8 offset:42240
	v_add_co_u32_e32 v6, vcc, s0, v4
	s_mov_b32 s0, 0x60000
	s_nop 0
	v_addc_co_u32_e32 v7, vcc, 0, v5, vcc
	s_waitcnt lgkmcnt(0)
	global_store_dwordx4 v[6:7], v[0:3], off
	ds_read_b128 v[0:3], v8 offset:50688
	v_add_co_u32_e32 v6, vcc, s0, v4
	s_mov_b32 s0, 0x70000
	s_nop 0
	v_addc_co_u32_e32 v7, vcc, 0, v5, vcc
	s_waitcnt lgkmcnt(0)
	global_store_dwordx4 v[6:7], v[0:3], off
	ds_read_b128 v[0:3], v8 offset:59136
	v_add_co_u32_e32 v4, vcc, s0, v4
	v_mov_b32_e32 v175, v179
	s_nop 0
	v_addc_co_u32_e32 v5, vcc, 0, v5, vcc
	s_waitcnt lgkmcnt(0)
	global_store_dwordx4 v[4:5], v[0:3], off
	s_barrier
	global_load_dword v4, v177, s[38:39] offset:4
	s_movk_i32 s0, 0xffe0
	v_ashrrev_i32_e32 v22, 2, v175
	v_bfi_b32 v0, s0, v22, v175
	v_ashrrev_i32_e32 v1, 31, v0
	v_bfe_u32 v24, v175, 5, 1
	v_lshlrev_b64 v[0:1], 12, v[0:1]
	v_lshl_add_u64 v[0:1], s[4:5], 0, v[0:1]
	v_lshlrev_b32_e32 v16, 4, v24
	v_mov_b32_e32 v17, v177
	v_lshl_add_u64 v[0:1], v[0:1], 0, v[16:17]
	global_load_dwordx4 v[82:85], v[0:1], off offset:256
	global_load_dwordx4 v[86:89], v[0:1], off offset:288
	global_load_dwordx4 v[90:93], v[0:1], off offset:320
	global_load_dwordx4 v[94:97], v[0:1], off offset:352
	global_load_dwordx4 v[98:101], v[0:1], off offset:384
	global_load_dwordx4 v[102:105], v[0:1], off offset:416
	global_load_dwordx4 v[106:109], v[0:1], off offset:448
	global_load_dwordx4 v[110:113], v[0:1], off offset:480
	v_and_b32_e32 v193, 63, v175
	v_ashrrev_i32_e32 v194, 6, v175
	v_lshlrev_b32_e32 v17, 4, v193
	v_lshlrev_b32_e32 v2, 10, v194
	v_or_b32_e32 v6, v2, v17
	v_and_b32_e32 v3, 15, v175
	v_ashrrev_i32_e32 v7, 8, v6
	v_bitop3_b32 v8, v7, v3, 7 bitop3:0x6c
	v_lshlrev_b32_e32 v7, 12, v7
	v_lshl_or_b32 v176, v8, 4, v7
	v_ashrrev_i32_e32 v7, 4, v6
	v_lshlrev_b32_e32 v8, 2, v194
	v_bfe_u32 v9, v7, 2, 2
	v_and_b32_e32 v8, 0xffff0, v8
	v_lshrrev_b32_e32 v7, 1, v7
	v_lshlrev_b32_e32 v10, 1, v194
	v_and_b32_e32 v7, 8, v7
	v_and_or_b32 v8, v10, 4, v8
	v_or3_b32 v7, v8, v9, v7
	v_lshrrev_b32_e32 v6, 3, v6
	v_and_b32_e32 v5, 48, v17
	v_and_b32_e32 v6, 0xc0, v6
	v_lshlrev_b32_e32 v7, 12, v7
	v_add_u32_e32 v2, 0x2000, v2
	v_or3_b32 v152, v7, v6, v5
	v_or_b32_e32 v6, v2, v17
	v_ashrrev_i32_e32 v7, 8, v6
	v_bitop3_b32 v3, v7, v3, 7 bitop3:0x6c
	v_lshlrev_b32_e32 v7, 12, v7
	v_lshl_or_b32 v154, v3, 4, v7
	v_ashrrev_i32_e32 v3, 4, v6
	v_ashrrev_i32_e32 v2, 8, v2
; DI float bf2f(u16 v) { return __uint_as_float(((unsigned)v) << 16); }
; DI int v_st(int k, int c) { const int kk = (k & ~0xC) | ((k & 4) << 1) | ((k & 8) >> 1); return ((kk >> 3) * 4 + (c >> 5)) * 512 + ((kk & 7) * 32 + (c & 31)) * 2; }
; DI int v_rd_base(int lane) { return ((lane & 3) << 3) | (((lane >> 2) & 3) << 6) | (((lane >> 4) & 1) << 5) | (((lane >> 5) & 1) << 8); }
; #define KDMA(k0, b) do { const char* g_ = (const char*)(Kh + (long)(k0) * DM); char* l_ = K_lds + (b) * 16384 + wu * 1024; \
;     DMA16(g_ + koff[0], l_); DMA16(g_ + koff[1], l_ + 8192); } while (0)
; template <int PROBE, int MODE>
; DI void dattn_body(const u16* __restrict__ Qb, const u16* __restrict__ Kh, const u16* __restrict__ Vh, u16* __restrict__ Ob, const u16* __restrict__ O1, float lam, const float* __restrict__ subg, int seq, int q0, float kmax2, char* lds) {
;     ...
;   float q2 = 0.f;
; #pragma unroll
;   for (int d0 = 0; d0 < 8; ++d0)
; #pragma unroll
;     for (int e = 0; e < 8; ++e) { const float f = bf2f((u16)qr[d0][e]); q2 = fmaf(f, f, q2); }
;   { auto rr = __builtin_amdgcn_permlane32_swap(__float_as_uint(q2), __float_as_uint(q2), false, false); q2 = __uint_as_float(rr[0]) + __uint_as_float(rr[1]); }
;   const int sr = tid >> 4, sc = (tid & 15) * 8, vst0 = v_st(sr, sc), vst1 = v_st(32 + sr, sc), kst0 = KSWZ(sr, sc * 2), kst1 = KSWZ(32 + sr, sc * 2);
;   const int vb0 = (int)(uintptr_t)V_lds + kh * 16384 + v_rd_base(lane);
;   const int qpos = q0 + rg * 32 + r32;
;   char* pw = P_lds + wid * 2048 + lane * 32;
;   const char* pr = P_lds + (wid ^ 1) * 2048 + lane * 32;
;   const int wu = __builtin_amdgcn_readfirstlane(wid);
;   unsigned koff[2], voff[2];
; #pragma unroll
;   for (int i = 0; i < 2; ++i) {
;     const int a = i * 8192 + wid * 1024 + lane * 16;
;     { const int row = a >> 8, pch = (a & 255) >> 4, c = pch ^ (row & 7); koff[i] = (unsigned)(row * DM + c * 8) * 2u; }
;     { const int q = a >> 4, sub = q >> 5, kk = (sub >> 2) * 8 + ((q & 31) >> 2), k = (kk & ~0xC) | ((kk & 4) << 1) | ((kk & 8) >> 1), col = (sub & 3) * 32 + (q & 3) * 8;
;       voff[i] = (unsigned)(k * DM + col) * 2u; }
;   }
;     ...
;   f32x16 o[4] = {}; f32x16 S; float l_reg = 0.f; bf16x8 po0, po1; const int NT = seq / KVBLK;
;   KDMA(0, 0); VDMA(0, 0); KDMA(KVBLK, 1);
	v_bfe_u32 v7, v3, 2, 2
	v_and_b32_e32 v8, 0xffff0, v2
	v_lshrrev_b32_e32 v3, 1, v3
	v_lshrrev_b32_e32 v2, 1, v2
	v_and_b32_e32 v3, 8, v3
	v_and_or_b32 v2, v2, 4, v8
	v_or3_b32 v2, v2, v7, v3
	v_lshrrev_b32_e32 v3, 3, v6
	v_readfirstlane_b32 s0, v194
	v_and_b32_e32 v3, 0xc0, v3
	v_lshlrev_b32_e32 v2, 12, v2
	s_lshl_b32 s0, s0, 10
	v_or3_b32 v156, v2, v3, v5
	s_add_i32 s38, s95, s0
	s_mov_b32 m0, s38
	s_add_i32 s39, s0, 16
	v_lshl_add_u64 v[2:3], s[16:17], 0, v[156:157]
	v_and_b32_e32 v192, 31, v175
	v_and_b32_e32 v195, 1, v194
	v_lshl_add_u64 v[8:9], s[14:15], 0, v[176:177]
	v_lshl_add_u64 v[8:9], v[8:9], 0, s[8:9]
	global_load_lds_dwordx4 v[8:9], off
	v_lshl_add_u64 v[8:9], s[14:15], 0, v[154:155]
	v_lshl_add_u64 v[8:9], v[8:9], 0, s[8:9]
	s_add_i32 m0, s38, 0x2000
	s_nop 0
	global_load_lds_dwordx4 v[8:9], off
	s_mov_b32 m0, s39
	v_lshl_add_u64 v[8:9], s[16:17], 0, v[152:153]
	global_load_lds_dwordx4 v152, s[16:17]
	s_add_i32 m0, s39, 0x2000
	v_lshl_add_u64 v[8:9], v[8:9], 0, s[8:9]
	global_load_lds_dwordx4 v156, s[16:17]
	s_add_i32 m0, s39, 0x4000
	s_nop 0
	global_load_lds_dwordx4 v[8:9], off
	s_add_i32 m0, s39, 0x6000
	v_lshl_add_u64 v[8:9], v[2:3], 0, s[8:9]
	s_add_u32 s0, s14, 0x40100
	global_load_lds_dwordx4 v[8:9], off
	s_addc_u32 s1, s15, 0
	s_add_i32 m0, s39, 0x14000
	s_nop 0
	global_load_lds_dwordx4 v176, s[0:1]
	s_add_i32 m0, s39, 0x16000
	s_nop 0
	global_load_lds_dwordx4 v154, s[0:1]
	s_waitcnt vmcnt(15)
	v_lshlrev_b32_e32 v0, 16, v82
	v_fma_f32 v0, v0, v0, 0
	v_and_b32_e32 v1, 0xffff0000, v82
	v_fmac_f32_e32 v0, v1, v1
	v_lshlrev_b32_e32 v1, 16, v83
	v_fmac_f32_e32 v0, v1, v1
	v_and_b32_e32 v1, 0xffff0000, v83
	v_fmac_f32_e32 v0, v1, v1
	v_lshlrev_b32_e32 v1, 16, v84
	v_fmac_f32_e32 v0, v1, v1
	v_and_b32_e32 v1, 0xffff0000, v84
	v_fmac_f32_e32 v0, v1, v1
	v_lshlrev_b32_e32 v1, 16, v85
	v_fmac_f32_e32 v0, v1, v1
	v_and_b32_e32 v1, 0xffff0000, v85
	v_fmac_f32_e32 v0, v1, v1
	s_waitcnt vmcnt(14)
	v_lshlrev_b32_e32 v1, 16, v86
	v_fmac_f32_e32 v0, v1, v1
	v_and_b32_e32 v1, 0xffff0000, v86
	v_fmac_f32_e32 v0, v1, v1
	v_lshlrev_b32_e32 v1, 16, v87
	v_fmac_f32_e32 v0, v1, v1
	v_and_b32_e32 v1, 0xffff0000, v87
	v_fmac_f32_e32 v0, v1, v1
	v_lshlrev_b32_e32 v1, 16, v88
	v_fmac_f32_e32 v0, v1, v1
	v_and_b32_e32 v1, 0xffff0000, v88
	v_fmac_f32_e32 v0, v1, v1
	v_lshlrev_b32_e32 v1, 16, v89
	v_fmac_f32_e32 v0, v1, v1
	v_and_b32_e32 v1, 0xffff0000, v89
	v_fmac_f32_e32 v0, v1, v1
	s_waitcnt vmcnt(13)
	v_lshlrev_b32_e32 v1, 16, v90
	v_fmac_f32_e32 v0, v1, v1
	v_and_b32_e32 v1, 0xffff0000, v90
	v_fmac_f32_e32 v0, v1, v1
	v_lshlrev_b32_e32 v1, 16, v91
	v_fmac_f32_e32 v0, v1, v1
	v_and_b32_e32 v1, 0xffff0000, v91
	v_fmac_f32_e32 v0, v1, v1
	v_lshlrev_b32_e32 v1, 16, v92
	v_fmac_f32_e32 v0, v1, v1
	v_and_b32_e32 v1, 0xffff0000, v92
	v_fmac_f32_e32 v0, v1, v1
	v_lshlrev_b32_e32 v1, 16, v93
	v_fmac_f32_e32 v0, v1, v1
	v_and_b32_e32 v1, 0xffff0000, v93
	v_fmac_f32_e32 v0, v1, v1
	s_waitcnt vmcnt(12)
	v_lshlrev_b32_e32 v1, 16, v94
	v_fmac_f32_e32 v0, v1, v1
	v_and_b32_e32 v1, 0xffff0000, v94
	v_fmac_f32_e32 v0, v1, v1
	v_lshlrev_b32_e32 v1, 16, v95
	v_fmac_f32_e32 v0, v1, v1
	v_and_b32_e32 v1, 0xffff0000, v95
	v_fmac_f32_e32 v0, v1, v1
	v_lshlrev_b32_e32 v1, 16, v96
	v_fmac_f32_e32 v0, v1, v1
	v_and_b32_e32 v1, 0xffff0000, v96
	v_fmac_f32_e32 v0, v1, v1
	v_lshlrev_b32_e32 v1, 16, v97
	v_fmac_f32_e32 v0, v1, v1
	v_and_b32_e32 v1, 0xffff0000, v97
	v_fmac_f32_e32 v0, v1, v1
	s_waitcnt vmcnt(11)
	v_lshlrev_b32_e32 v1, 16, v98
	v_fmac_f32_e32 v0, v1, v1
	v_and_b32_e32 v1, 0xffff0000, v98
	v_fmac_f32_e32 v0, v1, v1
	v_lshlrev_b32_e32 v1, 16, v99
	v_fmac_f32_e32 v0, v1, v1
	v_and_b32_e32 v1, 0xffff0000, v99
	v_fmac_f32_e32 v0, v1, v1
	v_lshlrev_b32_e32 v1, 16, v100
	v_fmac_f32_e32 v0, v1, v1
	v_and_b32_e32 v1, 0xffff0000, v100
	v_fmac_f32_e32 v0, v1, v1
	v_lshlrev_b32_e32 v1, 16, v101
	v_fmac_f32_e32 v0, v1, v1
	v_and_b32_e32 v1, 0xffff0000, v101
	v_fmac_f32_e32 v0, v1, v1
	s_waitcnt vmcnt(10)
	v_lshlrev_b32_e32 v1, 16, v102
	v_fmac_f32_e32 v0, v1, v1
	v_and_b32_e32 v1, 0xffff0000, v102
	v_fmac_f32_e32 v0, v1, v1
	v_lshlrev_b32_e32 v1, 16, v103
	v_fmac_f32_e32 v0, v1, v1
	v_and_b32_e32 v1, 0xffff0000, v103
	v_fmac_f32_e32 v0, v1, v1
	v_lshlrev_b32_e32 v1, 16, v104
	v_fmac_f32_e32 v0, v1, v1
	v_and_b32_e32 v1, 0xffff0000, v104
	v_fmac_f32_e32 v0, v1, v1
	v_lshlrev_b32_e32 v1, 16, v105
	v_fmac_f32_e32 v0, v1, v1
	v_and_b32_e32 v1, 0xffff0000, v105
	v_fmac_f32_e32 v0, v1, v1
	s_waitcnt vmcnt(9)
	v_lshlrev_b32_e32 v1, 16, v106
	v_fmac_f32_e32 v0, v1, v1
	v_and_b32_e32 v1, 0xffff0000, v106
	v_fmac_f32_e32 v0, v1, v1
	v_lshlrev_b32_e32 v1, 16, v107
	v_fmac_f32_e32 v0, v1, v1
	v_and_b32_e32 v1, 0xffff0000, v107
	v_fmac_f32_e32 v0, v1, v1
	v_lshlrev_b32_e32 v1, 16, v108
	v_fmac_f32_e32 v0, v1, v1
	v_and_b32_e32 v1, 0xffff0000, v108
	v_fmac_f32_e32 v0, v1, v1
	v_lshlrev_b32_e32 v1, 16, v109
	v_fmac_f32_e32 v0, v1, v1
	v_and_b32_e32 v1, 0xffff0000, v109
	v_fmac_f32_e32 v0, v1, v1
	s_waitcnt vmcnt(8)
	v_lshlrev_b32_e32 v1, 16, v110
	v_fmac_f32_e32 v0, v1, v1
	v_and_b32_e32 v1, 0xffff0000, v110
	v_fmac_f32_e32 v0, v1, v1
	v_lshlrev_b32_e32 v1, 16, v111
	v_fmac_f32_e32 v0, v1, v1
	v_and_b32_e32 v1, 0xffff0000, v111
	v_fmac_f32_e32 v0, v1, v1
	v_lshlrev_b32_e32 v1, 16, v112
	v_fmac_f32_e32 v0, v1, v1
	v_and_b32_e32 v1, 0xffff0000, v112
	v_fmac_f32_e32 v0, v1, v1
	v_lshlrev_b32_e32 v1, 16, v113
	v_fmac_f32_e32 v0, v1, v1
	v_and_b32_e32 v1, 0xffff0000, v113
	v_fmac_f32_e32 v0, v1, v1
	v_mov_b32_e32 v1, v0
	s_nop 1
	v_permlane32_swap_b32_e32 v0, v1
	v_add_f32_e32 v5, v0, v1
	v_mov_b32_e32 v0, s76
	s_waitcnt vmcnt(0)
	s_waitcnt vmcnt(0) lgkmcnt(0)
	s_barrier
; #define KDMA(k0, b) do { const char* g_ = (const char*)(Kh + (long)(k0) * DM); char* l_ = K_lds + (b) * 16384 + wu * 1024; \
;     DMA16(g_ + koff[0], l_); DMA16(g_ + koff[1], l_ + 8192); } while (0)
; #define VDMA(k0, b) do { const char* g_ = (const char*)(Vh + (long)(k0) * DM); char* l_ = V_lds + (b) * 32768 + wu * 1024; \
;     DMA16(g_ + voff[0], l_); DMA16(g_ + voff[1], l_ + 8192); DMA16(g_ + voff[0] + 256, l_ + 16384); DMA16(g_ + voff[1] + 256, l_ + 16384 + 8192); } while (0)
; #define DMAWAIT() asm volatile("s_waitcnt vmcnt(0)" ::: "memory")
; #define QKH(b) do { S = f32x16{}; const char* Ks_ = K_lds + (b) * 16384; _Pragma("unroll") for (int d0 = 0; d0 < 8; ++d0) { \
;     const bf16x8 kf = *reinterpret_cast<const bf16x8*>(Ks_ + KSWZ(32 * kh + r32, (d0 * 16 + hi * 8) * 2)); \
;     S = __builtin_amdgcn_mfma_f32_32x32x16_bf16(kf, qr[d0], S, 0, 0, 0); } } while (0)
; #define SMX_FIN(pbuf) do { _Pragma("unroll") for (int r = 0; r < 16; ++r) l_reg += S[r]; \
;     PK4S(0, po0); PK4S(8, po1); \
;     *(bf16x8*)(pw + (pbuf) * 16384) = po0; *(bf16x8*)(pw + (pbuf) * 16384 + 16) = po1; } while (0)
; template <int PROBE, int MODE>
; DI void dattn_body(const u16* __restrict__ Qb, const u16* __restrict__ Kh, const u16* __restrict__ Vh, u16* __restrict__ Ob, const u16* __restrict__ O1, float lam, const float* __restrict__ subg, int seq, int q0, float kmax2, char* lds) {
;     ...
;   f32x16 o[4] = {}; f32x16 S; float l_reg = 0.f; bf16x8 po0, po1; const int NT = seq / KVBLK;
;   KDMA(0, 0); VDMA(0, 0); KDMA(KVBLK, 1);
;   DMAWAIT();
;   __syncthreads();
;   const float biasL = __uint_as_float(__builtin_amdgcn_readfirstlane(__float_as_uint(tab[0]))), biasR = __uint_as_float(__builtin_amdgcn_readfirstlane(__float_as_uint(tab[256])));
;   const float Mrow = C * __builtin_sqrtf(q2 * kmax2) + tab[257];
;   QKH(0);
;   { SMX_SETUP(0) SMX_CH(0); SMX_CH(1); SMX_CH(2); SMX_CH(3); SMX_FIN(0); }
	ds_read_b32 v0, v0
	v_readlane_b32 s0, v255, 10
	s_waitcnt lgkmcnt(0)
	v_readfirstlane_b32 s20, v0
	v_mov_b32_e32 v0, s0
	ds_read_b64 v[18:19], v0
	v_mul_f32_e32 v0, v4, v5
	s_mov_b32 s0, 0xf800000
	v_cmp_gt_f32_e32 vcc, s0, v0
	v_mul_f32_e32 v1, 0x4f800000, v0
	s_waitcnt lgkmcnt(0)
	v_readfirstlane_b32 s21, v18
	v_cndmask_b32_e32 v0, v0, v1, vcc
	v_sqrt_f32_e32 v1, v0
	v_mov_b32_e32 v158, v19
	v_add_u32_e32 v2, -1, v1
	v_fma_f32 v3, -v2, v1, v0
	v_cmp_ge_f32_e64 s[0:1], 0, v3
	v_add_u32_e32 v3, 1, v1
	s_nop 0
	v_cndmask_b32_e64 v2, v1, v2, s[0:1]
	v_fma_f32 v1, -v3, v1, v0
	v_cmp_lt_f32_e64 s[0:1], 0, v1
	s_nop 1
	v_cndmask_b32_e64 v1, v2, v3, s[0:1]
	v_mul_f32_e32 v2, 0x37800000, v1
	v_cndmask_b32_e32 v1, v1, v2, vcc
	v_cmp_class_f32_e32 vcc, v0, v219
	v_lshlrev_b32_e32 v2, 4, v175
	s_movk_i32 s0, 0x70
	v_cndmask_b32_e32 v18, v1, v0, vcc
	v_lshlrev_b32_e32 v0, 13, v195
	v_lshlrev_b32_e32 v1, 8, v192
	v_add3_u32 v21, s95, v0, v1
	v_bitop3_b32 v196, v16, v2, s0 bitop3:0x78
	v_add_u32_e32 v0, v21, v196
	v_and_b32_e32 v20, 0x70, v2
	ds_read_b128 v[0:3], v0
	v_bitop3_b32 v198, v16, v20, 32 bitop3:0x36
	v_add_u32_e32 v23, v21, v198
	ds_read_b128 v[26:29], v23
	s_waitcnt lgkmcnt(1)
	v_mfma_f32_32x32x16_bf16 v[0:15], v[0:3], v[82:85], 0
	v_bitop3_b32 v199, v16, v20, 64 bitop3:0x36
	v_add_u32_e32 v23, v21, v199
	s_movk_i32 s0, 0x60
	v_bitop3_b32 v200, v16, v20, s0 bitop3:0x36
	v_bitop3_b32 v201, v16, v20, s22 bitop3:0x36
	s_movk_i32 s0, 0xa0
	v_bitop3_b32 v202, v16, v20, s0 bitop3:0x36
	s_waitcnt lgkmcnt(0)
	v_mfma_f32_32x32x16_bf16 v[0:15], v[26:29], v[86:89], v[0:15]
	ds_read_b128 v[26:29], v23
	v_add_u32_e32 v23, v21, v200
	s_movk_i32 s0, 0xc0
	v_bitop3_b32 v203, v16, v20, s0 bitop3:0x36
	s_movk_i32 s0, 0xe0
	v_bitop3_b32 v204, v16, v20, s0 bitop3:0x36
	v_add_u32_e32 v16, v21, v204
	s_waitcnt lgkmcnt(0)
	v_mfma_f32_32x32x16_bf16 v[0:15], v[26:29], v[90:93], v[0:15]
	ds_read_b128 v[26:29], v23
	v_add_u32_e32 v23, v21, v201
	v_fmac_f32_e32 v158, 0x3e0293ee, v18
	v_mov_b32_e32 v18, s21
	s_mov_b64 s[0:1], -1
	s_and_b64 vcc, exec, s[42:43]
	s_waitcnt lgkmcnt(0)
	v_mfma_f32_32x32x16_bf16 v[0:15], v[26:29], v[94:97], v[0:15]
	ds_read_b128 v[26:29], v23
	v_add_u32_e32 v23, v21, v202
	s_waitcnt lgkmcnt(0)
	v_mfma_f32_32x32x16_bf16 v[0:15], v[26:29], v[98:101], v[0:15]
	ds_read_b128 v[26:29], v23
	v_add_u32_e32 v23, v21, v203
	s_waitcnt lgkmcnt(0)
	v_mfma_f32_32x32x16_bf16 v[0:15], v[26:29], v[102:105], v[0:15]
	ds_read_b128 v[26:29], v23
	s_waitcnt lgkmcnt(0)
	v_mfma_f32_32x32x16_bf16 v[0:15], v[26:29], v[106:109], v[0:15]
	ds_read_b128 v[26:29], v16
	v_mov_b32_e32 v16, s20
	v_cndmask_b32_e64 v16, v16, v18, s[44:45]
	v_sub_f32_e32 v16, v16, v158
	s_waitcnt lgkmcnt(0)
	v_mfma_f32_32x32x16_bf16 v[0:15], v[26:29], v[110:113], v[0:15]
	s_cbranch_vccnz .LBB0_269
	s_nop 10
	v_pk_fma_f32 v[18:19], v[0:1], s[12:13], v[16:17] op_sel_hi:[1,0,0]
	v_pk_fma_f32 v[20:21], v[2:3], s[12:13], v[16:17] op_sel_hi:[1,0,0]
	s_mov_b64 s[0:1], 0
